# v70 + GEMM phase prologues: second K tile's 6 LDS-DMA loads issued right behind the first tile's 8 (first wait vmcnt(2) -> vmcnt(8), same loads retired), both tiles' latencies overlap; all six GEMM ph
# speedup vs baseline: 1.0118x; 1.0016x over previous
.LBB0_174:
	v_and_b32_e32 v144, 15, v10
	v_lshrrev_b32_e32 v10, 1, v10
	v_readlane_b32 s62, v254, 6
	v_and_b32_e32 v10, 24, v10
	s_lshl_b32 s18, s18, 5
	v_mov_b32_e32 v133, v153
	v_readlane_b32 s63, v254, 7
	v_lshlrev_b32_e32 v11, 1, v10
	v_lshlrev_b32_e32 v16, 2, v144
	s_and_b32 s21, s18, 0x60
	s_add_i32 m0, s68, 0x18000
	v_lshl_add_u64 v[0:1], v[0:1], 0, s[22:23]
	v_lshl_add_u64 v[12:13], s[62:63], 0, v[132:133]
	v_mov_b32_e32 v131, v153
	s_lshl_b32 s76, s19, 6
	v_lshl_or_b32 v11, v144, 6, v11
	s_lshl_b32 s19, s19, 13
	v_and_b32_e32 v17, 32, v16
	s_lshl_b32 s18, s21, 7
	global_load_lds_dwordx4 v[0:1], off
	v_lshl_add_u64 v[0:1], v[2:3], 0, s[22:23]
	s_add_i32 m0, s68, 0x1a000
	s_add_i32 s77, s68, 0x8000
	s_add_i32 s78, s68, 0xa000
	v_lshl_add_u64 v[14:15], s[62:63], 0, v[130:131]
	v_bitop3_b32 v145, v11, s18, v17 bitop3:0xde
	global_load_lds_dwordx4 v[0:1], off
	v_lshl_add_u64 v[0:1], v[12:13], 0, s[22:23]
	s_mov_b32 m0, s77
	s_add_u32 s18, s60, 0x40080
	v_bitop3_b32 v18, v11, s19, v17 bitop3:0xde
	global_load_lds_dwordx4 v[0:1], off
	v_lshl_add_u64 v[0:1], v[14:15], 0, s[22:23]
	s_mov_b32 m0, s78
	s_addc_u32 s19, s61, 0
	global_load_lds_dwordx4 v[0:1], off
	s_add_i32 m0, s68, 0x1c000
	v_lshl_add_u64 v[0:1], s[18:19], 0, v[152:153]
	global_load_lds_dwordx4 v[0:1], off
	v_lshl_add_u64 v[0:1], s[18:19], 0, v[128:129]
	s_add_i32 m0, s68, 0x1e000
	s_cmpk_lt_u32 s20, 0x100
	global_load_lds_dwordx4 v[0:1], off
	s_waitcnt vmcnt(8)
	s_barrier
	v_lshlrev_b32_e32 v0, 14, v4
	v_and_b32_e32 v0, 0xffff8000, v0
	v_lshl_add_u32 v0, v5, 11, v0
	v_and_b32_e32 v1, 1, v4
	v_lshl_or_b32 v0, v1, 6, v0
	s_cselect_b64 s[18:19], -1, 0
	s_and_b32 s20, s20, 0xffffff00
	v_lshl_add_u32 v134, v6, 1, v0
	v_lshlrev_b32_e32 v0, 14, v8
	s_add_i32 s20, s20, 0
	v_and_b32_e32 v0, 0xffff8000, v0
	s_waitcnt vmcnt(6)
	s_add_i32 s20, s20, 0x20400
	v_lshl_add_u32 v0, v7, 11, v0
	v_and_b32_e32 v1, 1, v8
	v_add_u32_e32 v146, s20, v16
	v_or_b32_e32 v147, s21, v10
	v_lshl_or_b32 v0, v1, 6, v0
	v_readlane_b32 s20, v253, 16
	v_mov_b32_e32 v135, v153
	v_lshl_add_u32 v136, v9, 1, v0
	v_mov_b32_e32 v137, v153
	s_mov_b32 s79, 0
	v_add_u32_e32 v148, 0, v18
	v_readlane_b32 s80, v253, 15
	s_mov_b32 s81, s20
	s_barrier
	v_readlane_b32 s21, v253, 17
	s_branch .LBB0_177

.LBB0_267:
	v_readlane_b32 s16, v253, 54
	s_or_b32 s8, s8, s16
	v_readlane_b32 s80, v251, 8
	s_cmp_eq_u32 s8, 0
	v_readlane_b32 s81, v251, 9
	s_cselect_b32 s17, s81, 0
	s_cselect_b32 s16, s80, 0
	v_bfe_u32 v13, v12, 4, 2
	v_readlane_b32 s60, v254, 38
	s_cmp_lg_u64 s[16:17], 0
	v_and_b32_e32 v18, 15, v12
	v_lshlrev_b32_e32 v20, 4, v13
	v_lshlrev_b32_e32 v12, 2, v12
	v_mov_b32_e32 v177, v153
	v_readlane_b32 s61, v254, 39
	s_cselect_b64 s[20:21], -1, 0
	s_and_b32 s78, s11, 3
	v_lshl_or_b32 v209, s10, 6, v18
	v_lshl_or_b32 v18, v18, 6, v20
	s_lshl_b32 s8, s10, 13
	v_and_b32_e32 v12, 32, v12
	s_add_i32 m0, s69, 0x18000
	v_lshl_add_u64 v[0:1], v[0:1], 0, s[22:23]
	v_lshl_add_u64 v[14:15], s[60:61], 0, v[176:177]
	v_mov_b32_e32 v175, v153
	v_bitop3_b32 v20, v18, s8, v12 bitop3:0xde
	s_lshl_b32 s8, s78, 12
	global_load_lds_dwordx4 v[0:1], off
	v_lshl_add_u64 v[0:1], v[2:3], 0, s[22:23]
	s_add_i32 m0, s69, 0x1a000
	s_add_i32 s79, s69, 0x8000
	s_add_i32 s80, s69, 0xa000
	v_lshl_add_u64 v[16:17], s[60:61], 0, v[174:175]
	global_load_lds_dwordx4 v[0:1], off
	v_lshl_add_u64 v[0:1], v[14:15], 0, s[22:23]
	s_mov_b32 m0, s79
	s_add_u32 s10, s18, 0xb0080
	global_load_lds_dwordx4 v[0:1], off
	v_lshl_add_u64 v[0:1], v[16:17], 0, s[22:23]
	s_mov_b32 m0, s80
	s_addc_u32 s11, s19, 0
	global_load_lds_dwordx4 v[0:1], off
	s_add_i32 m0, s69, 0x1c000
	v_lshl_add_u64 v[0:1], s[10:11], 0, v[152:153]
	global_load_lds_dwordx4 v[0:1], off
	v_lshl_add_u64 v[0:1], s[10:11], 0, v[172:173]
	s_add_i32 m0, s69, 0x1e000
	v_bitop3_b32 v210, v18, s8, v12 bitop3:0xde
	global_load_lds_dwordx4 v[0:1], off
	s_waitcnt vmcnt(8)
	s_barrier
	s_movk_i32 s8, 0xb00
	v_lshrrev_b32_e32 v1, 1, v4
	v_mul_lo_u32 v0, v5, s8
	s_mov_b32 s49, 0xb000
	s_cmpk_lt_u32 s44, 0x100
	v_mad_u64_u32 v[0:1], s[44:45], v1, s49, v[0:1]
	v_or_b32_e32 v0, v0, v6
	v_add_lshl_u32 v0, v0, v7, 1
	v_mov_b32_e32 v1, v153
	s_mov_b64 s[50:51], 0xb0080
	v_lshl_add_u64 v[178:179], v[0:1], 0, s[50:51]
	v_lshrrev_b32_e32 v1, 1, v9
	v_mul_lo_u32 v0, v8, s8
	v_readlane_b32 s94, v251, 22
	v_readlane_b32 s95, v251, 23
	v_mad_u64_u32 v[0:1], s[44:45], v1, s49, v[0:1]
	v_readlane_b32 s90, v251, 18
	v_readlane_b32 s91, v251, 19
	s_waitcnt vmcnt(6)
	v_or_b32_e32 v0, v0, v10
	v_readlane_b32 s94, v251, 33
	v_readlane_b32 s83, v251, 11
	v_readlane_b32 s88, v251, 16
	v_lshlrev_b32_e32 v19, 3, v13
	v_add_lshl_u32 v0, v0, v11, 1
	v_mov_b32_e32 v1, v153
	v_readlane_b32 s44, v253, 36
	v_readlane_b32 s95, v251, 34
	v_readlane_b32 s90, v251, 62
	s_mov_b32 s77, 0
	v_readlane_b32 s82, v251, 10
	v_lshl_or_b32 v211, s78, 5, v19
	s_cselect_b64 s[10:11], -1, 0
	v_cmp_eq_u32_e64 s[46:47], 0, v13
	v_lshl_add_u64 v[180:181], v[0:1], 0, s[50:51]
	v_add_u32_e32 v212, 0, v20
	v_readlane_b32 s83, v253, 22
	s_mov_b32 s8, s44
	v_readlane_b32 s91, v251, 63
	s_mov_b32 s95, s48
	v_readlane_b32 s88, v253, 49
	v_readlane_b32 s84, v251, 12
	v_readlane_b32 s85, v251, 13
	v_readlane_b32 s86, v251, 14
	v_readlane_b32 s87, v251, 15
	v_readlane_b32 s89, v251, 17
	v_readlane_b32 s92, v251, 20
	v_readlane_b32 s93, v251, 21
	s_barrier
	v_readlane_b32 s45, v253, 37
	s_branch .LBB0_270

.LBB0_413:
	v_and_b32_e32 v7, 15, v6
	v_lshrrev_b32_e32 v6, 1, v6
	v_readlane_b32 s48, v254, 50
	v_and_b32_e32 v16, 24, v6
	s_lshl_b32 s16, s16, 5
	v_readlane_b32 s49, v254, 51
	v_lshlrev_b32_e32 v6, 1, v16
	v_lshlrev_b32_e32 v17, 2, v7
	s_and_b32 s19, s16, 0x60
	v_lshl_add_u64 v[8:9], s[48:49], 0, v[152:153]
	v_mov_b32_e32 v145, v153
	v_readlane_b32 s44, v254, 46
	v_lshl_or_b32 v184, s17, 6, v7
	v_lshl_or_b32 v6, v7, 6, v6
	s_lshl_b32 s17, s17, 13
	v_and_b32_e32 v7, 32, v17
	s_lshl_b32 s16, s19, 7
	v_lshl_add_u64 v[10:11], s[48:49], 0, v[144:145]
	v_mov_b32_e32 v149, v153
	v_readlane_b32 s45, v254, 47
	v_bitop3_b32 v18, v6, s17, v7 bitop3:0xde
	v_bitop3_b32 v185, v6, s16, v7 bitop3:0xde
	s_add_i32 m0, s59, 0x18000
	v_lshl_add_u64 v[6:7], v[8:9], 0, s[22:23]
	v_lshl_add_u64 v[12:13], s[44:45], 0, v[148:149]
	v_mov_b32_e32 v147, v153
	global_load_lds_dwordx4 v[6:7], off
	v_lshl_add_u64 v[6:7], v[10:11], 0, s[22:23]
	s_add_i32 m0, s59, 0x1a000
	s_add_i32 s69, s59, 0x8000
	v_lshl_add_u64 v[14:15], s[44:45], 0, v[146:147]
	global_load_lds_dwordx4 v[6:7], off
	v_lshl_add_u64 v[6:7], v[12:13], 0, s[22:23]
	s_mov_b32 m0, s69
	s_add_i32 s74, s59, 0xa000
	v_readlane_b32 s16, v254, 52
	global_load_lds_dwordx4 v[6:7], off
	v_lshl_add_u64 v[6:7], v[14:15], 0, s[22:23]
	s_mov_b32 m0, s74
	v_readlane_b32 s17, v254, 53
	global_load_lds_dwordx4 v[6:7], off
	s_add_i32 m0, s59, 0x1c000
	v_lshl_add_u64 v[6:7], s[16:17], 0, v[152:153]
	global_load_lds_dwordx4 v[6:7], off
	v_lshl_add_u64 v[6:7], s[16:17], 0, v[144:145]
	s_add_i32 m0, s59, 0x1e000
	s_cmpk_lt_u32 s18, 0x100
	global_load_lds_dwordx4 v[6:7], off
	s_waitcnt vmcnt(8)
	s_barrier
	v_lshlrev_b32_e32 v6, 14, v0
	v_and_b32_e32 v6, 0xffff8000, v6
	v_lshl_add_u32 v1, v1, 11, v6
	v_and_b32_e32 v0, 1, v0
	v_lshl_or_b32 v0, v0, 6, v1
	s_cselect_b64 s[16:17], -1, 0
	s_and_b32 s18, s18, 0xffffff00
	v_lshl_add_u32 v150, v2, 1, v0
	v_lshlrev_b32_e32 v0, 14, v4
	s_add_i32 s18, s18, 0
	v_and_b32_e32 v0, 0xffff8000, v0
	s_waitcnt vmcnt(6)
	s_add_i32 s18, s18, 0x20400
	v_lshl_add_u32 v0, v3, 11, v0
	v_and_b32_e32 v1, 1, v4
	v_add_u32_e32 v186, s18, v17
	v_or_b32_e32 v187, s19, v16
	v_lshl_or_b32 v0, v1, 6, v0
	v_readlane_b32 s18, v253, 30
	v_mov_b32_e32 v151, v153
	v_lshl_add_u32 v172, v5, 1, v0
	v_mov_b32_e32 v173, v153
	s_mov_b32 s75, 0
	v_add_u32_e32 v188, 0, v18
	v_readlane_b32 s77, v253, 23
	s_mov_b32 s76, s18
	s_barrier
	v_readlane_b32 s19, v253, 31
	s_branch .LBB0_416

.LBB0_695:
	v_lshrrev_b32_e32 v16, 1, v6
	v_and_b32_e32 v16, 24, v16
	v_and_b32_e32 v7, 15, v6
	v_lshlrev_b32_e32 v17, 1, v16
	v_lshlrev_b32_e32 v6, 2, v6
	v_readlane_b32 s60, v254, 20
	v_lshl_or_b32 v194, s18, 6, v7
	v_lshl_or_b32 v7, v7, 6, v17
	s_lshl_b32 s18, s18, 13
	v_and_b32_e32 v6, 32, v6
	s_lshl_b32 s17, s17, 5
	v_readlane_b32 s61, v254, 21
	v_bitop3_b32 v17, v7, s18, v6 bitop3:0xde
	s_and_b32 s18, s17, 0x60
	v_lshl_add_u64 v[8:9], s[60:61], 0, v[152:153]
	v_mov_b32_e32 v173, v153
	v_readlane_b32 s44, v254, 16
	s_lshl_b32 s17, s18, 7
	v_lshl_add_u64 v[10:11], s[60:61], 0, v[172:173]
	v_mov_b32_e32 v177, v153
	v_readlane_b32 s45, v254, 17
	v_bitop3_b32 v195, v7, s17, v6 bitop3:0xde
	s_add_i32 m0, s59, 0x18000
	v_lshl_add_u64 v[6:7], v[8:9], 0, s[22:23]
	v_lshl_add_u64 v[12:13], s[44:45], 0, v[176:177]
	v_mov_b32_e32 v175, v153
	global_load_lds_dwordx4 v[6:7], off
	v_lshl_add_u64 v[6:7], v[10:11], 0, s[22:23]
	s_add_i32 m0, s59, 0x1a000
	s_add_i32 s69, s59, 0x8000
	v_lshl_add_u64 v[14:15], s[44:45], 0, v[174:175]
	global_load_lds_dwordx4 v[6:7], off
	v_lshl_add_u64 v[6:7], v[12:13], 0, s[22:23]
	s_mov_b32 m0, s69
	s_add_i32 s74, s59, 0xa000
	v_readlane_b32 s20, v254, 22
	global_load_lds_dwordx4 v[6:7], off
	v_lshl_add_u64 v[6:7], v[14:15], 0, s[22:23]
	s_mov_b32 m0, s74
	v_readlane_b32 s21, v254, 23
	global_load_lds_dwordx4 v[6:7], off
	s_add_i32 m0, s59, 0x1c000
	v_lshl_add_u64 v[6:7], s[20:21], 0, v[152:153]
	global_load_lds_dwordx4 v[6:7], off
	v_lshl_add_u64 v[6:7], s[20:21], 0, v[172:173]
	s_add_i32 m0, s59, 0x1e000
	s_cmpk_lt_u32 s16, 0x100
	global_load_lds_dwordx4 v[6:7], off
	s_waitcnt vmcnt(8)
	s_barrier
	v_lshlrev_b32_e32 v6, 13, v0
	v_and_b32_e32 v6, 0xffffc000, v6
	v_lshl_add_u32 v1, v1, 10, v6
	v_and_b32_e32 v0, 1, v0
	v_lshl_or_b32 v0, v0, 6, v1
	v_lshl_add_u32 v178, v2, 1, v0
	v_lshlrev_b32_e32 v0, 13, v4
	v_and_b32_e32 v0, 0xffffc000, v0
	s_waitcnt vmcnt(6)
	v_lshl_add_u32 v0, v3, 10, v0
	v_and_b32_e32 v1, 1, v4
	v_or_b32_e32 v196, s18, v16
	v_lshl_or_b32 v0, v1, 6, v0
	v_readlane_b32 s18, v253, 36
	s_cselect_b64 s[16:17], -1, 0
	v_mov_b32_e32 v179, v153
	v_lshl_add_u32 v180, v5, 1, v0
	v_mov_b32_e32 v181, v153
	s_mov_b32 s75, 0
	v_add_u32_e32 v197, 0, v17
	v_readlane_b32 s76, v253, 22
	s_mov_b32 s77, s18
	s_barrier
	v_readlane_b32 s19, v253, 37
	s_branch .LBB0_698

.LBB0_715:
	v_lshrrev_b32_e32 v16, 1, v6
	v_and_b32_e32 v16, 24, v16
	v_and_b32_e32 v7, 15, v6
	v_lshlrev_b32_e32 v17, 1, v16
	v_lshlrev_b32_e32 v6, 2, v6
	v_readlane_b32 s60, v254, 34
	v_lshl_or_b32 v180, s18, 6, v7
	v_lshl_or_b32 v7, v7, 6, v17
	s_lshl_b32 s18, s18, 13
	v_and_b32_e32 v6, 32, v6
	s_lshl_b32 s17, s17, 5
	v_readlane_b32 s61, v254, 35
	v_bitop3_b32 v17, v7, s18, v6 bitop3:0xde
	s_and_b32 s18, s17, 0x60
	v_lshl_add_u64 v[8:9], s[60:61], 0, v[152:153]
	v_mov_b32_e32 v145, v153
	v_readlane_b32 s44, v254, 30
	s_lshl_b32 s17, s18, 7
	v_lshl_add_u64 v[10:11], s[60:61], 0, v[144:145]
	v_mov_b32_e32 v149, v153
	v_readlane_b32 s45, v254, 31
	v_bitop3_b32 v181, v7, s17, v6 bitop3:0xde
	s_add_i32 m0, s59, 0x18000
	v_lshl_add_u64 v[6:7], v[8:9], 0, s[22:23]
	v_lshl_add_u64 v[12:13], s[44:45], 0, v[148:149]
	v_mov_b32_e32 v147, v153
	global_load_lds_dwordx4 v[6:7], off
	v_lshl_add_u64 v[6:7], v[10:11], 0, s[22:23]
	s_add_i32 m0, s59, 0x1a000
	s_add_i32 s69, s59, 0x8000
	v_lshl_add_u64 v[14:15], s[44:45], 0, v[146:147]
	global_load_lds_dwordx4 v[6:7], off
	v_lshl_add_u64 v[6:7], v[12:13], 0, s[22:23]
	s_mov_b32 m0, s69
	s_add_i32 s74, s59, 0xa000
	v_readlane_b32 s20, v254, 36
	global_load_lds_dwordx4 v[6:7], off
	v_lshl_add_u64 v[6:7], v[14:15], 0, s[22:23]
	s_mov_b32 m0, s74
	v_readlane_b32 s21, v254, 37
	global_load_lds_dwordx4 v[6:7], off
	s_add_i32 m0, s59, 0x1c000
	v_lshl_add_u64 v[6:7], s[20:21], 0, v[152:153]
	global_load_lds_dwordx4 v[6:7], off
	v_lshl_add_u64 v[6:7], s[20:21], 0, v[144:145]
	s_add_i32 m0, s59, 0x1e000
	s_cmpk_lt_u32 s16, 0x100
	global_load_lds_dwordx4 v[6:7], off
	s_waitcnt vmcnt(8)
	s_barrier
	v_lshlrev_b32_e32 v6, 13, v0
	v_and_b32_e32 v6, 0xffffc000, v6
	v_lshl_add_u32 v1, v1, 10, v6
	v_and_b32_e32 v0, 1, v0
	v_lshl_or_b32 v0, v0, 6, v1
	v_lshl_add_u32 v150, v2, 1, v0
	v_lshlrev_b32_e32 v0, 13, v4
	v_and_b32_e32 v0, 0xffffc000, v0
	s_waitcnt vmcnt(6)
	v_lshl_add_u32 v0, v3, 10, v0
	v_and_b32_e32 v1, 1, v4
	v_or_b32_e32 v182, s18, v16
	v_lshl_or_b32 v0, v1, 6, v0
	v_readlane_b32 s18, v253, 36
	s_cselect_b64 s[16:17], -1, 0
	v_mov_b32_e32 v151, v153
	v_lshl_add_u32 v172, v5, 1, v0
	v_mov_b32_e32 v173, v153
	s_mov_b32 s75, 0
	v_add_u32_e32 v183, 0, v17
	v_readlane_b32 s76, v253, 22
	s_mov_b32 s77, s18
	s_barrier
	v_readlane_b32 s19, v253, 37
	s_branch .LBB0_718

.LBB0_812:
	v_bfe_u32 v16, v6, 4, 2
	v_readlane_b32 s62, v254, 62
	v_and_b32_e32 v7, 15, v6
	v_lshlrev_b32_e32 v18, 4, v16
	v_lshlrev_b32_e32 v6, 2, v6
	v_readlane_b32 s63, v254, 63
	s_and_b32 s76, s16, 3
	v_lshl_or_b32 v209, s17, 6, v7
	v_lshl_or_b32 v7, v7, 6, v18
	s_lshl_b32 s16, s17, 13
	v_and_b32_e32 v6, 32, v6
	v_lshl_add_u64 v[8:9], s[62:63], 0, v[152:153]
	v_mov_b32_e32 v173, v153
	v_readlane_b32 s60, v254, 58
	v_bitop3_b32 v18, v7, s16, v6 bitop3:0xde
	s_lshl_b32 s16, s76, 12
	v_lshl_add_u64 v[10:11], s[62:63], 0, v[172:173]
	v_mov_b32_e32 v177, v153
	v_readlane_b32 s61, v254, 59
	v_bitop3_b32 v210, v7, s16, v6 bitop3:0xde
	s_add_i32 m0, s68, 0x18000
	v_lshl_add_u64 v[6:7], v[8:9], 0, s[22:23]
	v_lshl_add_u64 v[12:13], s[60:61], 0, v[176:177]
	v_mov_b32_e32 v175, v153
	global_load_lds_dwordx4 v[6:7], off
	v_lshl_add_u64 v[6:7], v[10:11], 0, s[22:23]
	s_add_i32 m0, s68, 0x1a000
	s_add_i32 s77, s68, 0x8000
	v_lshl_add_u64 v[14:15], s[60:61], 0, v[174:175]
	global_load_lds_dwordx4 v[6:7], off
	v_lshl_add_u64 v[6:7], v[12:13], 0, s[22:23]
	s_mov_b32 m0, s77
	s_add_i32 s78, s68, 0xa000
	v_readlane_b32 s16, v250, 0
	global_load_lds_dwordx4 v[6:7], off
	v_lshl_add_u64 v[6:7], v[14:15], 0, s[22:23]
	s_mov_b32 m0, s78
	v_readlane_b32 s17, v250, 1
	global_load_lds_dwordx4 v[6:7], off
	s_add_i32 m0, s68, 0x1c000
	v_lshl_add_u64 v[6:7], s[16:17], 0, v[152:153]
	global_load_lds_dwordx4 v[6:7], off
	v_lshl_add_u64 v[6:7], s[16:17], 0, v[172:173]
	s_add_i32 m0, s68, 0x1e000
	v_lshlrev_b32_e32 v17, 3, v16
	global_load_lds_dwordx4 v[6:7], off
	s_waitcnt vmcnt(8)
	s_barrier
	v_lshlrev_b32_e32 v6, 14, v0
	v_and_b32_e32 v6, 0xffff8000, v6
	v_lshl_add_u32 v1, v1, 11, v6
	v_and_b32_e32 v0, 1, v0
	v_lshl_or_b32 v0, v0, 6, v1
	v_lshl_add_u32 v178, v2, 1, v0
	v_lshlrev_b32_e32 v0, 14, v4
	v_and_b32_e32 v0, 0xffff8000, v0
	s_waitcnt vmcnt(6)
	v_lshl_add_u32 v0, v3, 11, v0
	v_and_b32_e32 v1, 1, v4
	s_cmpk_lt_u32 s8, 0x100
	v_lshl_or_b32 v0, v1, 6, v0
	v_readlane_b32 s18, v253, 36
	v_lshl_or_b32 v211, s76, 5, v17
	s_cselect_b64 s[16:17], -1, 0
	s_mov_b32 s79, 0
	v_cmp_eq_u32_e64 s[44:45], 0, v16
	v_mov_b32_e32 v179, v153
	v_lshl_add_u32 v180, v5, 1, v0
	v_mov_b32_e32 v181, v153
	v_add_u32_e32 v212, 0, v18
	v_readlane_b32 s8, v253, 22
	s_mov_b32 s80, s18
	s_barrier
	v_readlane_b32 s19, v253, 37
	s_branch .LBB0_815
